# attention staging: per-iteration full vmcnt drain replaced by counted waits (set A/B loads stay in flight across the iteration edge)
# baseline (speedup 1.0000x reference)
.Lattn_nocalcA:
	s_waitcnt vmcnt(4)
	s_cmp_gt_i32 s76, s3
	s_cbranch_scc0 .Lattn_h1w
	s_waitcnt vmcnt(0)
.Lattn_h1w:
	ds_write_b128 v237, v[148:151] offset:32768
	ds_write_b128 v238, v[156:159] offset:32768
	s_barrier
	s_waitcnt vmcnt(4)
	s_cmp_ge_i32 s76, s3
	s_cselect_b64 s[0:1], -1, 0
	s_and_b64 vcc, exec, s[0:1]
	ds_write_b128 v239, v[144:147]
	ds_write_b128 v240, v[152:155]
	s_waitcnt lgkmcnt(0)
	s_barrier
	s_cbranch_vccnz .LBB0_328
	global_load_dwordx4 v[144:147], v[214:215], off offset:2048
	global_load_dwordx4 v[148:151], v[214:215], off offset:1024
	global_load_dwordx4 v[152:155], v[216:217], off offset:2048
	global_load_dwordx4 v[156:159], v[216:217], off offset:1024

.Lattn_kwB:
	ds_write_b128 v237, v[164:167] offset:49152
	ds_write_b128 v238, v[172:175] offset:49152
	s_barrier
	s_waitcnt vmcnt(4)
	s_and_b64 vcc, exec, s[0:1]
	ds_write_b128 v239, v[160:163] offset:16384
	ds_write_b128 v240, v[168:171] offset:16384
	s_waitcnt lgkmcnt(0)
	s_barrier
	s_cbranch_vccnz .LBB0_336
	s_mov_b32 s33, s76
	s_add_i32 s0, s33, 1
	s_cmp_ge_i32 s0, s3
	s_cbranch_scc1 .LBB0_326
	global_load_dwordx4 v[160:163], v[214:215], off offset:2048
	global_load_dwordx4 v[164:167], v[214:215], off offset:1024
	global_load_dwordx4 v[168:171], v[216:217], off offset:2048
	global_load_dwordx4 v[172:175], v[216:217], off offset:1024
	s_branch .LBB0_326
